# attention: one static s_setprio 1 for waves 4-7, per-cluster setprio toggles removed (on top of v5)
# speedup vs baseline: 1.0078x; 1.0078x over previous
.LBB0_663:
	s_setprio 0
	ds_bpermute_b32 v0, v198, v201
	v_lshlrev_b64 v[2:3], 10, v[182:183]
	s_lshl_b32 s46, s62, 1
	v_lshl_add_u64 v[2:3], s[44:45], 0, v[2:3]
	v_lshl_add_u64 v[2:3], v[2:3], 0, s[46:47]
	s_waitcnt lgkmcnt(0)
	v_add_f32_e32 v0, v201, v0
	v_div_scale_f32 v4, s[2:3], v0, v0, 1.0
	v_rcp_f32_e32 v5, v4
	v_div_scale_f32 v6, vcc, 1.0, v0, 1.0
	v_mov_b32_e32 v49, v1
	v_fma_f32 v7, -v4, v5, 1.0
	v_fmac_f32_e32 v5, v7, v5
	v_mul_f32_e32 v7, v6, v5
	v_fma_f32 v8, -v4, v7, v6
	v_fmac_f32_e32 v7, v8, v5
	v_fma_f32 v4, -v4, v7, v6
	v_div_fmas_f32 v4, v4, v5, v7
	v_div_fixup_f32 v0, v4, v0, 1.0
	v_mul_f32_e32 v4, v64, v0
	v_mul_f32_e32 v5, v65, v0
	v_cvt_pk_bf16_f32 v4, v4, v5
	v_mul_f32_e32 v5, v66, v0
	v_lshl_add_u64 v[2:3], v[48:49], 1, v[2:3]
	v_mul_f32_e32 v6, v67, v0
	v_cvt_pk_bf16_f32 v5, v5, v6
	global_store_dwordx2 v[2:3], v[4:5], off
	v_mul_f32_e32 v4, v32, v0
	v_mul_f32_e32 v5, v33, v0
	v_cvt_pk_bf16_f32 v4, v4, v5
	v_mul_f32_e32 v5, v34, v0
	v_mul_f32_e32 v6, v35, v0
	v_cvt_pk_bf16_f32 v5, v5, v6
	global_store_dwordx2 v[2:3], v[4:5], off offset:64
	v_mul_f32_e32 v4, v68, v0
	v_mul_f32_e32 v5, v69, v0
	v_cvt_pk_bf16_f32 v4, v4, v5
	v_mul_f32_e32 v5, v70, v0
	v_mul_f32_e32 v6, v71, v0
	v_cvt_pk_bf16_f32 v5, v5, v6
	global_store_dwordx2 v[2:3], v[4:5], off offset:16
	v_mul_f32_e32 v4, v36, v0
	v_mul_f32_e32 v5, v37, v0
	v_cvt_pk_bf16_f32 v4, v4, v5
	v_mul_f32_e32 v5, v38, v0
	v_mul_f32_e32 v6, v39, v0
	v_cvt_pk_bf16_f32 v5, v5, v6
	global_store_dwordx2 v[2:3], v[4:5], off offset:80
	v_mul_f32_e32 v4, v72, v0
	v_mul_f32_e32 v5, v73, v0
	v_cvt_pk_bf16_f32 v4, v4, v5
	v_mul_f32_e32 v5, v74, v0
	v_mul_f32_e32 v6, v75, v0
	v_cvt_pk_bf16_f32 v5, v5, v6
	global_store_dwordx2 v[2:3], v[4:5], off offset:32
	v_mul_f32_e32 v4, v40, v0
	v_mul_f32_e32 v5, v41, v0
	v_cvt_pk_bf16_f32 v4, v4, v5
	v_mul_f32_e32 v5, v42, v0
	v_mul_f32_e32 v6, v43, v0
	v_cvt_pk_bf16_f32 v5, v5, v6
	global_store_dwordx2 v[2:3], v[4:5], off offset:96
	v_mul_f32_e32 v4, v76, v0
	v_mul_f32_e32 v5, v77, v0
	v_cvt_pk_bf16_f32 v4, v4, v5
	v_mul_f32_e32 v5, v78, v0
	v_mul_f32_e32 v6, v79, v0
	v_cvt_pk_bf16_f32 v5, v5, v6
	global_store_dwordx2 v[2:3], v[4:5], off offset:48
	v_mul_f32_e32 v4, v44, v0
	v_mul_f32_e32 v5, v45, v0
	s_add_i32 s61, s61, s80
	v_cvt_pk_bf16_f32 v4, v4, v5
	v_mul_f32_e32 v5, v46, v0
	s_cmpk_lt_i32 s61, 0x800
	v_mul_f32_e32 v0, v47, v0
	v_cvt_pk_bf16_f32 v5, v5, v0
	global_store_dwordx2 v[2:3], v[4:5], off offset:112
	s_cbranch_scc0 .LBB0_699

.LBB0_672:
	s_andn2_b64 vcc, exec, s[2:3]
	s_cbranch_vccnz .LBB0_698
	v_max_f32_e32 v3, v5, v5
	v_mul_u32_u24_e32 v2, 0x90, v2
	v_max_f32_e32 v199, v4, v3
	v_add3_u32 v200, 0, v2, v0
	v_sub_f32_e32 v0, v16, v199
	v_exp_f32_e32 v16, v0
	v_sub_f32_e32 v0, v17, v199
	v_exp_f32_e32 v17, v0
	v_sub_f32_e32 v0, v18, v199
	v_exp_f32_e32 v18, v0
	v_sub_f32_e32 v0, v19, v199
	v_exp_f32_e32 v19, v0
	v_sub_f32_e32 v0, v20, v199
	v_exp_f32_e32 v20, v0
	v_sub_f32_e32 v0, v21, v199
	v_exp_f32_e32 v21, v0
	v_sub_f32_e32 v0, v22, v199
	v_exp_f32_e32 v22, v0
	v_sub_f32_e32 v0, v23, v199
	v_exp_f32_e32 v23, v0
	v_sub_f32_e32 v0, v24, v199
	v_exp_f32_e32 v24, v0
	v_sub_f32_e32 v0, v25, v199
	v_exp_f32_e32 v25, v0
	v_sub_f32_e32 v0, v26, v199
	v_exp_f32_e32 v26, v0
	v_sub_f32_e32 v0, v27, v199
	v_exp_f32_e32 v27, v0
	v_sub_f32_e32 v0, v28, v199
	v_exp_f32_e32 v28, v0
	v_sub_f32_e32 v0, v29, v199
	v_exp_f32_e32 v29, v0
	v_sub_f32_e32 v0, v30, v199
	v_exp_f32_e32 v30, v0
	v_sub_f32_e32 v0, v31, v199
	v_exp_f32_e32 v31, v0
	v_sub_f32_e32 v0, v32, v199
	v_exp_f32_e32 v80, v0
	v_sub_f32_e32 v0, v33, v199
	v_exp_f32_e32 v81, v0
	v_sub_f32_e32 v0, v34, v199
	v_exp_f32_e32 v82, v0
	v_sub_f32_e32 v0, v35, v199
	v_exp_f32_e32 v83, v0
	v_sub_f32_e32 v0, v36, v199
	v_exp_f32_e32 v84, v0
	v_sub_f32_e32 v0, v37, v199
	v_exp_f32_e32 v85, v0
	v_sub_f32_e32 v0, v38, v199
	v_exp_f32_e32 v86, v0
	v_sub_f32_e32 v0, v39, v199
	v_exp_f32_e32 v87, v0
	v_sub_f32_e32 v0, v40, v199
	v_exp_f32_e32 v88, v0
	v_sub_f32_e32 v0, v41, v199
	v_exp_f32_e32 v89, v0
	v_sub_f32_e32 v0, v42, v199
	v_exp_f32_e32 v90, v0
	v_sub_f32_e32 v0, v43, v199
	v_exp_f32_e32 v91, v0
	v_sub_f32_e32 v0, v44, v199
	v_exp_f32_e32 v92, v0
	v_sub_f32_e32 v0, v45, v199
	v_exp_f32_e32 v93, v0
	v_sub_f32_e32 v0, v46, v199
	v_exp_f32_e32 v94, v0
	v_sub_f32_e32 v0, v47, v199
	v_exp_f32_e32 v95, v0
	v_mov_b32_e32 v14, v1
	v_mov_b32_e32 v15, v1
	s_lshl_b32 s64, s4, 2
	v_xor_b32_e32 v48, 0x80000000, v199
	v_mov_b32_e32 v0, v1
	v_mov_b32_e32 v2, v1
	v_mov_b32_e32 v3, v1
	v_mov_b32_e32 v4, v1
	v_mov_b32_e32 v5, v1
	v_mov_b32_e32 v6, v1
	v_mov_b32_e32 v7, v1
	v_mov_b32_e32 v8, v1
	v_mov_b32_e32 v9, v1
	v_mov_b32_e32 v10, v1
	v_mov_b32_e32 v11, v1
	v_mov_b32_e32 v12, v1
	v_mov_b32_e32 v13, v1
	v_mov_b64_e32 v[46:47], v[14:15]
	v_mov_b64_e32 v[78:79], v[14:15]
	s_ashr_i32 s65, s63, 6
	v_mov_b32_e32 v49, v48
	v_mov_b32_e32 v50, v48
	v_mov_b32_e32 v51, v48
	v_mov_b32_e32 v52, v48
	v_mov_b32_e32 v53, v48
	v_mov_b32_e32 v54, v48
	v_mov_b32_e32 v55, v48
	v_mov_b32_e32 v56, v48
	v_mov_b32_e32 v57, v48
	v_mov_b32_e32 v58, v48
	v_mov_b32_e32 v59, v48
	v_mov_b32_e32 v60, v48
	v_mov_b32_e32 v61, v48
	v_mov_b32_e32 v62, v48
	v_mov_b32_e32 v63, v48
	s_or_b32 s66, s64, 3
	s_mov_b32 s67, 0
	v_mov_b32_e32 v201, 0
	s_movk_i32 s68, 0xbf
	v_mov_b64_e32 v[44:45], v[12:13]
	v_mov_b64_e32 v[42:43], v[10:11]
	v_mov_b64_e32 v[40:41], v[8:9]
	v_mov_b64_e32 v[38:39], v[6:7]
	v_mov_b64_e32 v[36:37], v[4:5]
	v_mov_b64_e32 v[34:35], v[2:3]
	v_mov_b64_e32 v[32:33], v[0:1]
	v_mov_b64_e32 v[76:77], v[12:13]
	v_mov_b64_e32 v[74:75], v[10:11]
	v_mov_b64_e32 v[72:73], v[8:9]
	v_mov_b64_e32 v[70:71], v[6:7]
	v_mov_b64_e32 v[68:69], v[4:5]
	v_mov_b64_e32 v[66:67], v[2:3]
	v_mov_b64_e32 v[64:65], v[0:1]
	s_bitcmp1_b32 s63, 7
	s_cbranch_scc0 .Latt_prio_done
	s_setprio 1
.Latt_prio_done:
.LBB0_674:
	s_add_i32 s2, s67, -1
	s_and_b32 s2, s2, 3
	s_mulk_i32 s2, 0x3400
	s_and_b32 s71, s67, 2
	s_add_i32 s2, s2, 0
	s_xor_b32 s3, s71, 2
	v_add_u32_e32 v0, s2, v192
	s_mulk_i32 s3, 0x2400
	s_waitcnt vmcnt(5)
	ds_write_b128 v0, v[152:155]
	v_add_u32_e32 v0, s2, v185
	s_add_i32 s2, s67, 5
	s_waitcnt vmcnt(4)
	ds_write_b128 v0, v[156:159] offset:128
	v_add_u32_e32 v0, s3, v193
	s_min_i32 s46, s2, s66
	s_add_i32 s2, s67, 4
	v_add_u32_e32 v0, 0xd000, v0
	s_min_i32 s2, s2, s66
	s_lshl_b64 s[4:5], s[46:47], 16
	s_mov_b32 s3, s47
	s_waitcnt vmcnt(3)
	ds_write2_b64 v0, v[172:173], v[174:175] offset1:2
	v_lshl_add_u64 v[2:3], v[186:187], 0, s[4:5]
	s_lshl_b64 s[4:5], s[46:47], 12
	s_lshl_b64 s[2:3], s[2:3], 7
	v_lshl_add_u64 v[4:5], v[188:189], 0, s[4:5]
	global_load_dwordx4 v[152:155], v[2:3], off
	global_load_dwordx4 v[156:159], v[4:5], off
	v_lshl_add_u64 v[2:3], v[190:191], 0, s[2:3]
	global_load_dwordx4 v[172:175], v[2:3], off
	s_add_i32 s70, s67, 1
	s_and_b32 s69, s70, 3
	s_cmp_gt_i32 s67, s65
	s_cbranch_scc1 .LBB0_685
	s_mul_i32 s2, s69, 0x3400
	v_add_u32_e32 v0, s2, v196
	ds_read_b128 v[2:5], v0
	ds_read_b128 v[6:9], v0 offset:6656
	s_waitcnt lgkmcnt(1)
	v_mfma_f32_32x32x16_bf16 v[112:127], v[2:5], v[128:131], v[48:63]
	ds_read_b128 v[10:13], v0 offset:32
	ds_read_b128 v[202:205], v0 offset:6688
	v_add_f32_e32 v14, 0, v80
	v_add_f32_e32 v14, v81, v14
	v_cvt_pk_bf16_f32 v176, v80, v81
	s_waitcnt lgkmcnt(2)
	v_mfma_f32_32x32x16_bf16 v[96:111], v[6:9], v[128:131], v[48:63]
	v_add_f32_e32 v2, v82, v14
	v_add_f32_e32 v2, v83, v2
	v_add_f32_e32 v14, v84, v2
	v_cvt_pk_bf16_f32 v177, v82, v83
	s_waitcnt lgkmcnt(1)
	v_mfma_f32_32x32x16_bf16 v[112:127], v[10:13], v[132:135], v[112:127]
	ds_read_b128 v[2:5], v0 offset:64
	ds_read_b128 v[6:9], v0 offset:6720
	v_add_f32_e32 v14, v85, v14
	v_add_f32_e32 v14, v86, v14
	v_add_f32_e32 v14, v87, v14
	v_cvt_pk_bf16_f32 v178, v84, v85
	v_cvt_pk_bf16_f32 v179, v86, v87
	s_waitcnt lgkmcnt(2)
	v_mfma_f32_32x32x16_bf16 v[96:111], v[202:205], v[132:135], v[96:111]
	v_add_f32_e32 v10, v88, v14
	v_add_f32_e32 v11, v89, v10
	v_cvt_pk_bf16_f32 v10, v88, v89
	s_waitcnt lgkmcnt(1)
	v_mfma_f32_32x32x16_bf16 v[112:127], v[2:5], v[136:139], v[112:127]
	ds_read_b128 v[80:83], v0 offset:96
	ds_read_b128 v[202:205], v0 offset:6752
	v_add_f32_e32 v11, v90, v11
	v_add_f32_e32 v11, v91, v11
	v_add_f32_e32 v12, v92, v11
	v_cvt_pk_bf16_f32 v11, v90, v91
	s_waitcnt lgkmcnt(2)
	v_mfma_f32_32x32x16_bf16 v[96:111], v[6:9], v[136:139], v[96:111]
	v_add_f32_e32 v2, v93, v12
	v_add_f32_e32 v2, v94, v2
	v_add_f32_e32 v14, v95, v2
	v_cvt_pk_bf16_f32 v12, v92, v93
	v_cvt_pk_bf16_f32 v13, v94, v95
	s_waitcnt lgkmcnt(1)
	v_mfma_f32_32x32x16_bf16 v[112:127], v[80:83], v[140:143], v[112:127]
	ds_read_b128 v[2:5], v0 offset:128
	ds_read_b128 v[206:209], v0 offset:6784
	v_add_f32_e32 v6, v16, v14
	v_add_f32_e32 v7, v17, v6
	v_cvt_pk_bf16_f32 v6, v16, v17
	s_waitcnt lgkmcnt(2)
	v_mfma_f32_32x32x16_bf16 v[96:111], v[202:205], v[140:143], v[96:111]
	v_add_f32_e32 v7, v18, v7
	v_add_f32_e32 v7, v19, v7
	v_add_f32_e32 v8, v20, v7
	v_cvt_pk_bf16_f32 v7, v18, v19
	s_waitcnt lgkmcnt(1)
	v_mfma_f32_32x32x16_bf16 v[112:127], v[2:5], v[144:147], v[112:127]
	ds_read_b128 v[14:17], v0 offset:160
	ds_read_b128 v[80:83], v0 offset:6816
	v_add_f32_e32 v0, v21, v8
	v_add_f32_e32 v0, v22, v0
	v_add_f32_e32 v0, v23, v0
	v_cvt_pk_bf16_f32 v8, v20, v21
	v_cvt_pk_bf16_f32 v9, v22, v23
	s_waitcnt lgkmcnt(2)
	v_mfma_f32_32x32x16_bf16 v[96:111], v[206:209], v[144:147], v[96:111]
	v_add_f32_e32 v0, v24, v0
	v_add_f32_e32 v0, v25, v0
	v_cvt_pk_bf16_f32 v2, v24, v25
	s_waitcnt lgkmcnt(1)
	v_mfma_f32_32x32x16_bf16 v[112:127], v[14:17], v[148:151], v[112:127]
	v_add_f32_e32 v0, v26, v0
	v_add_f32_e32 v0, v27, v0
	v_add_f32_e32 v0, v28, v0
	v_cvt_pk_bf16_f32 v3, v26, v27
	s_waitcnt lgkmcnt(0)
	v_mfma_f32_32x32x16_bf16 v[96:111], v[80:83], v[148:151], v[96:111]
	v_add_f32_e32 v0, v29, v0
	v_add_f32_e32 v0, v30, v0
	v_add_f32_e32 v0, v31, v0
	v_cvt_pk_bf16_f32 v4, v28, v29
	v_cvt_pk_bf16_f32 v5, v30, v31
	s_mul_i32 s4, s71, 0x2400
	v_add_u32_e32 v206, s4, v200
	ds_read_b128 v[16:19], v206 offset:53248
	ds_read_b128 v[202:205], v206 offset:57856
	s_cmp_ge_i32 s67, s65
	v_add_f32_e32 v201, v201, v0
	s_cbranch_scc1 .LBB0_682
	s_sub_i32 s2, s68, 64
	s_cmp_le_i32 s2, s63
	s_cbranch_scc1 .LBB0_680
	v_add_u32_e32 v0, s68, v197
	v_add_u32_e32 v15, 0xffffffa1, v0
	v_add_u32_e32 v14, 0xffffff81, v0
	v_cmp_le_i32_e64 s[2:3], v15, v184
	v_cmp_le_i32_e32 vcc, v14, v184
	s_nop 0
	v_cndmask_b32_e64 v96, v194, v96, s[2:3]
	v_cmp_lt_i32_e64 s[2:3], v14, v184
	v_add_u32_e32 v14, 0xffffffa2, v0
	v_cmp_le_i32_e64 s[4:5], v14, v184
	v_add_u32_e32 v14, 0xffffff83, v0
	s_nop 0
	v_cndmask_b32_e64 v97, v194, v97, s[4:5]
	v_cmp_le_i32_e64 s[4:5], v14, v184
	v_add_u32_e32 v14, 0xffffffa3, v0
	v_cmp_le_i32_e64 s[6:7], v14, v184
	v_add_u32_e32 v14, 0xffffff84, v0
	s_nop 0
	v_cndmask_b32_e64 v98, v194, v98, s[6:7]
	v_cmp_le_i32_e64 s[6:7], v14, v184
	v_add_u32_e32 v14, 0xffffffa4, v0
	v_cmp_le_i32_e64 s[8:9], v14, v184
	v_add_u32_e32 v14, 0xffffff89, v0
	s_nop 0
	v_cndmask_b32_e64 v99, v194, v99, s[8:9]
	v_cmp_le_i32_e64 s[8:9], v14, v184
	v_add_u32_e32 v14, 0xffffffa9, v0
	v_cmp_le_i32_e64 s[10:11], v14, v184
	v_add_u32_e32 v14, 0xffffff8a, v0
	s_nop 0
	v_cndmask_b32_e64 v100, v194, v100, s[10:11]
	v_cmp_le_i32_e64 s[10:11], v14, v184
	v_add_u32_e32 v14, 0xffffffaa, v0
	v_cmp_le_i32_e64 s[12:13], v14, v184
	v_add_u32_e32 v14, 0xffffff8b, v0
	s_nop 0
	v_cndmask_b32_e64 v101, v194, v101, s[12:13]
	v_cmp_le_i32_e64 s[12:13], v14, v184
	v_add_u32_e32 v14, 0xffffffab, v0
	v_cmp_le_i32_e64 s[14:15], v14, v184
	v_add_u32_e32 v14, 0xffffff8c, v0
	s_nop 0
	v_cndmask_b32_e64 v102, v194, v102, s[14:15]
	v_cmp_le_i32_e64 s[14:15], v14, v184
	v_add_u32_e32 v14, 0xffffffac, v0
	v_cmp_le_i32_e64 s[16:17], v14, v184
	v_add_u32_e32 v14, 0xffffff91, v0
	s_nop 0
	v_cndmask_b32_e64 v103, v194, v103, s[16:17]
	v_cmp_le_i32_e64 s[16:17], v14, v184
	v_add_u32_e32 v14, 0xffffffb1, v0
	v_cmp_le_i32_e64 s[18:19], v14, v184
	v_add_u32_e32 v14, 0xffffff92, v0
	s_nop 0
	v_cndmask_b32_e64 v104, v194, v104, s[18:19]
	v_cmp_le_i32_e64 s[18:19], v14, v184
	v_add_u32_e32 v14, 0xffffffb2, v0
	v_cmp_le_i32_e64 s[20:21], v14, v184
	v_add_u32_e32 v14, 0xffffff93, v0
	s_nop 0
	v_cndmask_b32_e64 v105, v194, v105, s[20:21]
	v_cmp_le_i32_e64 s[20:21], v14, v184
	v_add_u32_e32 v14, 0xffffffb3, v0
	v_cmp_le_i32_e64 s[22:23], v14, v184
	v_add_u32_e32 v14, 0xffffff94, v0
	s_nop 0
	v_cndmask_b32_e64 v106, v194, v106, s[22:23]
	v_cmp_le_i32_e64 s[22:23], v14, v184
	v_add_u32_e32 v14, 0xffffffb4, v0
	v_cmp_le_i32_e64 s[24:25], v14, v184
	v_add_u32_e32 v14, 0xffffff99, v0
	s_nop 0
	v_cndmask_b32_e64 v107, v194, v107, s[24:25]
	v_cmp_le_i32_e64 s[24:25], v14, v184
	v_add_u32_e32 v14, 0xffffffb9, v0
	v_cmp_le_i32_e64 s[26:27], v14, v184
	v_add_u32_e32 v14, 0xffffff9a, v0
	s_nop 0
	v_cndmask_b32_e64 v108, v194, v108, s[26:27]
	v_cmp_le_i32_e64 s[26:27], v14, v184
	v_add_u32_e32 v14, 0xffffffba, v0
	v_cmp_le_i32_e64 s[28:29], v14, v184
	v_add_u32_e32 v14, 0xffffff9b, v0
	s_nop 0
	v_cndmask_b32_e64 v109, v194, v109, s[28:29]
	v_cmp_le_i32_e64 s[28:29], v14, v184
	v_add_u32_e32 v14, 0xffffffbb, v0
	v_cmp_le_i32_e64 s[30:31], v14, v184
	v_add_u32_e32 v14, 0xffffff9c, v0
	v_add_u32_e32 v0, 0xffffffbc, v0
	v_cndmask_b32_e64 v110, v194, v110, s[30:31]
	v_cmp_le_i32_e64 s[30:31], v14, v184
	v_cmp_gt_i32_e64 s[34:35], v0, v184
	s_and_saveexec_b64 s[48:49], s[34:35]
	v_mov_b32_e32 v111, s59
	s_or_b64 exec, exec, s[48:49]
	v_cndmask_b32_e64 v113, v194, v113, s[2:3]
	v_cndmask_b32_e32 v112, v194, v112, vcc
	v_cndmask_b32_e64 v114, v194, v114, s[4:5]
	v_cndmask_b32_e64 v115, v194, v115, s[6:7]
	v_cndmask_b32_e64 v116, v194, v116, s[8:9]
	v_cndmask_b32_e64 v117, v194, v117, s[10:11]
	v_cndmask_b32_e64 v118, v194, v118, s[12:13]
	v_cndmask_b32_e64 v119, v194, v119, s[14:15]
	v_cndmask_b32_e64 v120, v194, v120, s[16:17]
	v_cndmask_b32_e64 v121, v194, v121, s[18:19]
	v_cndmask_b32_e64 v122, v194, v122, s[20:21]
	v_cndmask_b32_e64 v123, v194, v123, s[22:23]
	v_cndmask_b32_e64 v124, v194, v124, s[24:25]
	v_cndmask_b32_e64 v125, v194, v125, s[26:27]
	v_cndmask_b32_e64 v126, v194, v126, s[28:29]
	v_cndmask_b32_e64 v127, v194, v127, s[30:31]

.LBB0_683:
	s_waitcnt lgkmcnt(1)
	v_mfma_f32_32x32x16_bf16 v[64:79], v[16:19], v[176:179], v[64:79]
	v_exp_f32_e32 v80, v112
	v_exp_f32_e32 v81, v113
	v_exp_f32_e32 v82, v114
	v_exp_f32_e32 v83, v115
	ds_read_b128 v[112:115], v206 offset:53280
	s_waitcnt lgkmcnt(1)
	v_mfma_f32_32x32x16_bf16 v[32:47], v[202:205], v[176:179], v[32:47]
	ds_read_b128 v[14:17], v206 offset:57888
	v_exp_f32_e32 v84, v116
	v_exp_f32_e32 v85, v117
	v_exp_f32_e32 v86, v118
	v_exp_f32_e32 v87, v119
	s_waitcnt lgkmcnt(1)
	v_mfma_f32_32x32x16_bf16 v[64:79], v[112:115], v[10:13], v[64:79]
	ds_read_b128 v[116:119], v206 offset:53312
	v_exp_f32_e32 v88, v120
	v_exp_f32_e32 v89, v121
	v_exp_f32_e32 v90, v122
	v_exp_f32_e32 v91, v123
	s_waitcnt lgkmcnt(1)
	v_mfma_f32_32x32x16_bf16 v[32:47], v[14:17], v[10:13], v[32:47]
	ds_read_b128 v[112:115], v206 offset:57920
	v_exp_f32_e32 v92, v124
	v_exp_f32_e32 v93, v125
	v_exp_f32_e32 v94, v126
	v_exp_f32_e32 v95, v127
	s_waitcnt lgkmcnt(1)
	v_mfma_f32_32x32x16_bf16 v[64:79], v[116:119], v[6:9], v[64:79]
	ds_read_b128 v[10:13], v206 offset:53344
	v_exp_f32_e32 v16, v96
	v_exp_f32_e32 v17, v97
	v_exp_f32_e32 v18, v98
	v_exp_f32_e32 v19, v99
	s_waitcnt lgkmcnt(1)
	v_mfma_f32_32x32x16_bf16 v[32:47], v[112:115], v[6:9], v[32:47]
	ds_read_b128 v[96:99], v206 offset:57952
	v_exp_f32_e32 v20, v100
	v_exp_f32_e32 v21, v101
	v_exp_f32_e32 v22, v102
	v_exp_f32_e32 v23, v103
	s_waitcnt lgkmcnt(1)
	v_mfma_f32_32x32x16_bf16 v[64:79], v[10:13], v[2:5], v[64:79]
	v_exp_f32_e32 v24, v104
	v_exp_f32_e32 v25, v105
	v_exp_f32_e32 v26, v106
	v_exp_f32_e32 v27, v107
	s_waitcnt lgkmcnt(0)
	v_mfma_f32_32x32x16_bf16 v[32:47], v[96:99], v[2:5], v[32:47]
	v_exp_f32_e32 v28, v108
	v_exp_f32_e32 v29, v109
	v_exp_f32_e32 v30, v110
	v_exp_f32_e32 v31, v111
	s_andn2_b64 vcc, exec, s[2:3]
	s_cbranch_vccnz .LBB0_685
	v_pk_mul_f32 v[78:79], v[0:1], v[78:79] op_sel_hi:[0,1]
	v_pk_mul_f32 v[76:77], v[0:1], v[76:77] op_sel_hi:[0,1]
	v_pk_mul_f32 v[74:75], v[0:1], v[74:75] op_sel_hi:[0,1]
	v_pk_mul_f32 v[72:73], v[0:1], v[72:73] op_sel_hi:[0,1]
	v_pk_mul_f32 v[70:71], v[0:1], v[70:71] op_sel_hi:[0,1]
	v_pk_mul_f32 v[68:69], v[0:1], v[68:69] op_sel_hi:[0,1]
	v_pk_mul_f32 v[66:67], v[0:1], v[66:67] op_sel_hi:[0,1]
	v_pk_mul_f32 v[64:65], v[0:1], v[64:65] op_sel_hi:[0,1]
	v_pk_mul_f32 v[46:47], v[0:1], v[46:47] op_sel_hi:[0,1]
	v_pk_mul_f32 v[44:45], v[0:1], v[44:45] op_sel_hi:[0,1]
	v_pk_mul_f32 v[42:43], v[0:1], v[42:43] op_sel_hi:[0,1]
	v_pk_mul_f32 v[40:41], v[0:1], v[40:41] op_sel_hi:[0,1]
	v_pk_mul_f32 v[38:39], v[0:1], v[38:39] op_sel_hi:[0,1]
	v_pk_mul_f32 v[36:37], v[0:1], v[36:37] op_sel_hi:[0,1]
	v_pk_mul_f32 v[34:35], v[0:1], v[34:35] op_sel_hi:[0,1]
	v_pk_mul_f32 v[32:33], v[0:1], v[32:33] op_sel_hi:[0,1]
.LBB0_685:
	s_mulk_i32 s71, 0x3400
	s_add_i32 s3, s71, 0
	s_xor_b32 s2, s69, 2
	v_add_u32_e32 v0, s3, v192
	s_mulk_i32 s2, 0x2400
	s_waitcnt vmcnt(5)
	ds_write_b128 v0, v[168:171]
	v_add_u32_e32 v0, s3, v185
	s_waitcnt vmcnt(4)
	ds_write_b128 v0, v[164:167] offset:128
	v_add_u32_e32 v0, s2, v193
	s_add_i32 s2, s67, 6
	s_min_i32 s2, s2, s66
	s_mov_b32 s3, s47
	v_add_u32_e32 v0, 0xd000, v0
	s_lshl_b64 s[4:5], s[2:3], 16
	s_lshl_b64 s[2:3], s[2:3], 12
	s_waitcnt vmcnt(3)
	ds_write2_b64 v0, v[160:161], v[162:163] offset1:2
	v_lshl_add_u64 v[2:3], v[186:187], 0, s[4:5]
	v_lshl_add_u64 v[4:5], v[188:189], 0, s[2:3]
	s_lshl_b64 s[2:3], s[46:47], 7
	global_load_dwordx4 v[168:171], v[2:3], off
	global_load_dwordx4 v[164:167], v[4:5], off
	v_lshl_add_u64 v[2:3], v[190:191], 0, s[2:3]
	global_load_dwordx4 v[160:163], v[2:3], off
	s_add_i32 s46, s67, 2
	s_cmp_ge_i32 s67, s65
	s_cbranch_scc1 .LBB0_696
	s_and_b32 s2, s46, 2
	s_mulk_i32 s2, 0x3400
	v_add_u32_e32 v0, s2, v196
	ds_read_b128 v[2:5], v0
	ds_read_b128 v[6:9], v0 offset:6656
	s_waitcnt lgkmcnt(1)
	v_mfma_f32_32x32x16_bf16 v[112:127], v[2:5], v[128:131], v[48:63]
	ds_read_b128 v[10:13], v0 offset:32
	ds_read_b128 v[202:205], v0 offset:6688
	v_add_f32_e32 v14, 0, v80
	v_add_f32_e32 v14, v81, v14
	v_cvt_pk_bf16_f32 v176, v80, v81
	s_waitcnt lgkmcnt(2)
	v_mfma_f32_32x32x16_bf16 v[96:111], v[6:9], v[128:131], v[48:63]
	v_add_f32_e32 v2, v82, v14
	v_add_f32_e32 v2, v83, v2
	v_add_f32_e32 v14, v84, v2
	v_cvt_pk_bf16_f32 v177, v82, v83
	s_waitcnt lgkmcnt(1)
	v_mfma_f32_32x32x16_bf16 v[112:127], v[10:13], v[132:135], v[112:127]
	ds_read_b128 v[2:5], v0 offset:64
	ds_read_b128 v[6:9], v0 offset:6720
	v_add_f32_e32 v14, v85, v14
	v_add_f32_e32 v14, v86, v14
	v_add_f32_e32 v14, v87, v14
	v_cvt_pk_bf16_f32 v178, v84, v85
	v_cvt_pk_bf16_f32 v179, v86, v87
	s_waitcnt lgkmcnt(2)
	v_mfma_f32_32x32x16_bf16 v[96:111], v[202:205], v[132:135], v[96:111]
	v_add_f32_e32 v10, v88, v14
	v_add_f32_e32 v11, v89, v10
	v_cvt_pk_bf16_f32 v10, v88, v89
	s_waitcnt lgkmcnt(1)
	v_mfma_f32_32x32x16_bf16 v[112:127], v[2:5], v[136:139], v[112:127]
	ds_read_b128 v[80:83], v0 offset:96
	ds_read_b128 v[202:205], v0 offset:6752
	v_add_f32_e32 v11, v90, v11
	v_add_f32_e32 v11, v91, v11
	v_add_f32_e32 v12, v92, v11
	v_cvt_pk_bf16_f32 v11, v90, v91
	s_waitcnt lgkmcnt(2)
	v_mfma_f32_32x32x16_bf16 v[96:111], v[6:9], v[136:139], v[96:111]
	v_add_f32_e32 v2, v93, v12
	v_add_f32_e32 v2, v94, v2
	v_add_f32_e32 v14, v95, v2
	v_cvt_pk_bf16_f32 v12, v92, v93
	v_cvt_pk_bf16_f32 v13, v94, v95
	s_waitcnt lgkmcnt(1)
	v_mfma_f32_32x32x16_bf16 v[112:127], v[80:83], v[140:143], v[112:127]
	ds_read_b128 v[2:5], v0 offset:128
	ds_read_b128 v[206:209], v0 offset:6784
	v_add_f32_e32 v6, v16, v14
	v_add_f32_e32 v7, v17, v6
	v_cvt_pk_bf16_f32 v6, v16, v17
	s_waitcnt lgkmcnt(2)
	v_mfma_f32_32x32x16_bf16 v[96:111], v[202:205], v[140:143], v[96:111]
	v_add_f32_e32 v7, v18, v7
	v_add_f32_e32 v7, v19, v7
	v_add_f32_e32 v8, v20, v7
	v_cvt_pk_bf16_f32 v7, v18, v19
	s_waitcnt lgkmcnt(1)
	v_mfma_f32_32x32x16_bf16 v[112:127], v[2:5], v[144:147], v[112:127]
	ds_read_b128 v[14:17], v0 offset:160
	ds_read_b128 v[80:83], v0 offset:6816
	v_add_f32_e32 v0, v21, v8
	v_add_f32_e32 v0, v22, v0
	v_add_f32_e32 v0, v23, v0
	v_cvt_pk_bf16_f32 v8, v20, v21
	v_cvt_pk_bf16_f32 v9, v22, v23
	s_waitcnt lgkmcnt(2)
	v_mfma_f32_32x32x16_bf16 v[96:111], v[206:209], v[144:147], v[96:111]
	v_add_f32_e32 v0, v24, v0
	v_add_f32_e32 v0, v25, v0
	v_cvt_pk_bf16_f32 v2, v24, v25
	s_waitcnt lgkmcnt(1)
	v_mfma_f32_32x32x16_bf16 v[112:127], v[14:17], v[148:151], v[112:127]
	v_add_f32_e32 v0, v26, v0
	v_add_f32_e32 v0, v27, v0
	v_add_f32_e32 v0, v28, v0
	v_cvt_pk_bf16_f32 v3, v26, v27
	s_waitcnt lgkmcnt(0)
	v_mfma_f32_32x32x16_bf16 v[96:111], v[80:83], v[148:151], v[96:111]
	v_add_f32_e32 v0, v29, v0
	v_add_f32_e32 v0, v30, v0
	v_add_f32_e32 v0, v31, v0
	v_cvt_pk_bf16_f32 v4, v28, v29
	v_cvt_pk_bf16_f32 v5, v30, v31
	s_mul_i32 s4, s69, 0x2400
	v_add_u32_e32 v206, s4, v200
	ds_read_b128 v[16:19], v206 offset:53248
	ds_read_b128 v[202:205], v206 offset:57856
	s_cmp_ge_i32 s70, s65
	v_add_f32_e32 v201, v201, v0
	s_cbranch_scc1 .LBB0_693
	s_cmp_le_i32 s68, s63
	s_cbranch_scc1 .LBB0_691
	v_add_u32_e32 v0, s68, v197
	v_subrev_u32_e32 v15, 31, v0
	v_subrev_u32_e32 v14, 63, v0
	v_cmp_le_i32_e64 s[2:3], v15, v184
	v_cmp_le_i32_e32 vcc, v14, v184
	s_nop 0
	v_cndmask_b32_e64 v96, v194, v96, s[2:3]
	v_cmp_lt_i32_e64 s[2:3], v14, v184
	v_subrev_u32_e32 v14, 30, v0
	v_cmp_le_i32_e64 s[4:5], v14, v184
	v_subrev_u32_e32 v14, 61, v0
	s_nop 0
	v_cndmask_b32_e64 v97, v194, v97, s[4:5]
	v_cmp_le_i32_e64 s[4:5], v14, v184
	v_subrev_u32_e32 v14, 29, v0
	v_cmp_le_i32_e64 s[6:7], v14, v184
	v_subrev_u32_e32 v14, 60, v0
	s_nop 0
	v_cndmask_b32_e64 v98, v194, v98, s[6:7]
	v_cmp_le_i32_e64 s[6:7], v14, v184
	v_subrev_u32_e32 v14, 28, v0
	v_cmp_le_i32_e64 s[8:9], v14, v184
	v_subrev_u32_e32 v14, 55, v0
	s_nop 0
	v_cndmask_b32_e64 v99, v194, v99, s[8:9]
	v_cmp_le_i32_e64 s[8:9], v14, v184
	v_subrev_u32_e32 v14, 23, v0
	v_cmp_le_i32_e64 s[10:11], v14, v184
	v_subrev_u32_e32 v14, 54, v0
	s_nop 0
	v_cndmask_b32_e64 v100, v194, v100, s[10:11]
	v_cmp_le_i32_e64 s[10:11], v14, v184
	v_subrev_u32_e32 v14, 22, v0
	v_cmp_le_i32_e64 s[12:13], v14, v184
	v_subrev_u32_e32 v14, 53, v0
	s_nop 0
	v_cndmask_b32_e64 v101, v194, v101, s[12:13]
	v_cmp_le_i32_e64 s[12:13], v14, v184
	v_subrev_u32_e32 v14, 21, v0
	v_cmp_le_i32_e64 s[14:15], v14, v184
	v_subrev_u32_e32 v14, 52, v0
	s_nop 0
	v_cndmask_b32_e64 v102, v194, v102, s[14:15]
	v_cmp_le_i32_e64 s[14:15], v14, v184
	v_subrev_u32_e32 v14, 20, v0
	v_cmp_le_i32_e64 s[16:17], v14, v184
	v_subrev_u32_e32 v14, 47, v0
	s_nop 0
	v_cndmask_b32_e64 v103, v194, v103, s[16:17]
	v_cmp_le_i32_e64 s[16:17], v14, v184
	v_add_u32_e32 v14, -15, v0
	v_cmp_le_i32_e64 s[18:19], v14, v184
	v_subrev_u32_e32 v14, 46, v0
	s_nop 0
	v_cndmask_b32_e64 v104, v194, v104, s[18:19]
	v_cmp_le_i32_e64 s[18:19], v14, v184
	v_add_u32_e32 v14, -14, v0
	v_cmp_le_i32_e64 s[20:21], v14, v184
	v_subrev_u32_e32 v14, 45, v0
	s_nop 0
	v_cndmask_b32_e64 v105, v194, v105, s[20:21]
	v_cmp_le_i32_e64 s[20:21], v14, v184
	v_add_u32_e32 v14, -13, v0
	v_cmp_le_i32_e64 s[22:23], v14, v184
	v_subrev_u32_e32 v14, 44, v0
	s_nop 0
	v_cndmask_b32_e64 v106, v194, v106, s[22:23]
	v_cmp_le_i32_e64 s[22:23], v14, v184
	v_add_u32_e32 v14, -12, v0
	v_cmp_le_i32_e64 s[24:25], v14, v184
	v_subrev_u32_e32 v14, 39, v0
	s_nop 0
	v_cndmask_b32_e64 v107, v194, v107, s[24:25]
	v_cmp_le_i32_e64 s[24:25], v14, v184
	v_add_u32_e32 v14, -7, v0
	v_cmp_le_i32_e64 s[26:27], v14, v184
	v_subrev_u32_e32 v14, 38, v0
	s_nop 0
	v_cndmask_b32_e64 v108, v194, v108, s[26:27]
	v_cmp_le_i32_e64 s[26:27], v14, v184
	v_add_u32_e32 v14, -6, v0
	v_cmp_le_i32_e64 s[28:29], v14, v184
	v_subrev_u32_e32 v14, 37, v0
	s_nop 0
	v_cndmask_b32_e64 v109, v194, v109, s[28:29]
	v_cmp_le_i32_e64 s[28:29], v14, v184
	v_add_u32_e32 v14, -5, v0
	v_cmp_le_i32_e64 s[30:31], v14, v184
	v_subrev_u32_e32 v14, 36, v0
	v_add_u32_e32 v0, -4, v0
	v_cndmask_b32_e64 v110, v194, v110, s[30:31]
	v_cmp_le_i32_e64 s[30:31], v14, v184
	v_cmp_gt_i32_e64 s[34:35], v0, v184
	s_and_saveexec_b64 s[48:49], s[34:35]
	v_mov_b32_e32 v111, s59
	s_or_b64 exec, exec, s[48:49]
	v_cndmask_b32_e64 v113, v194, v113, s[2:3]
	v_cndmask_b32_e32 v112, v194, v112, vcc
	v_cndmask_b32_e64 v114, v194, v114, s[4:5]
	v_cndmask_b32_e64 v115, v194, v115, s[6:7]
	v_cndmask_b32_e64 v116, v194, v116, s[8:9]
	v_cndmask_b32_e64 v117, v194, v117, s[10:11]
	v_cndmask_b32_e64 v118, v194, v118, s[12:13]
	v_cndmask_b32_e64 v119, v194, v119, s[14:15]
	v_cndmask_b32_e64 v120, v194, v120, s[16:17]
	v_cndmask_b32_e64 v121, v194, v121, s[18:19]
	v_cndmask_b32_e64 v122, v194, v122, s[20:21]
	v_cndmask_b32_e64 v123, v194, v123, s[22:23]
	v_cndmask_b32_e64 v124, v194, v124, s[24:25]
	v_cndmask_b32_e64 v125, v194, v125, s[26:27]
	v_cndmask_b32_e64 v126, v194, v126, s[28:29]
	v_cndmask_b32_e64 v127, v194, v127, s[30:31]
